# gemm_in silu/sigmoid epilogue: batched exp/rcp (16 independent values per stage), scalar silu select, 16-byte stores via permlane16_swap
# speedup vs baseline: 1.0121x; 1.0097x over previous
; DI unsigned pk2(float a, float b) { f32x2 v = {a, b}; bfv2 r = __builtin_convertvector(v, bfv2); return __builtin_bit_cast(unsigned, r); }
; DI float sigmoidf_(float x) { return __builtin_amdgcn_rcpf(1.0f + __expf(-x)); }
; DI float siluf_(float x) { return x * __builtin_amdgcn_rcpf(1.0f + __expf(-x)); }
; DI void phase_gemm_in(const Params& p, int l, char* lds) {
;     ...
;       } else if (kind == 1 || kind == 5) {
; #pragma unroll
;         for (int ni = 0; ni < 4; ++ni) {
;           const int c = colb + ni * 16; f32x4 v = acc[mi][ni];
; #pragma unroll
;           for (int e = 0; e < 4; ++e) v[e] = (kind == 1) ? siluf_(v[e]) : sigmoidf_(v[e]);
;           u32x2 o; o[0] = pk2(v[0], v[1]); o[1] = pk2(v[2], v[3]); *(u32x2*)(zrow + c) = o;
;         }
.LBB0_95:
	s_andn2_b64 vcc, exec, s[0:1]
	s_cbranch_vccnz .LBB0_97
	v_mov_b32_e32 v75, v1
	v_lshl_add_u64 v[66:67], v[74:75], 1, v[76:77]
	v_bfe_u32 v68, v212, 4, 1
	v_mov_b32_e32 v69, 0
	v_mul_u32_u24_e32 v68, 24, v68
	v_lshl_add_u64 v[66:67], v[68:69], 0, v[66:67]
	v_mul_f32_e32 v112, 0xbfb8aa3b, v54
	v_mul_f32_e32 v113, 0xbfb8aa3b, v55
	v_mul_f32_e32 v114, 0xbfb8aa3b, v56
	v_mul_f32_e32 v115, 0xbfb8aa3b, v57
	v_mul_f32_e32 v116, 0xbfb8aa3b, v50
	v_mul_f32_e32 v117, 0xbfb8aa3b, v51
	v_mul_f32_e32 v118, 0xbfb8aa3b, v52
	v_mul_f32_e32 v119, 0xbfb8aa3b, v53
	v_mul_f32_e32 v120, 0xbfb8aa3b, v58
	v_mul_f32_e32 v121, 0xbfb8aa3b, v59
	v_mul_f32_e32 v122, 0xbfb8aa3b, v60
	v_mul_f32_e32 v123, 0xbfb8aa3b, v61
	v_mul_f32_e32 v124, 0xbfb8aa3b, v62
	v_mul_f32_e32 v125, 0xbfb8aa3b, v63
	v_mul_f32_e32 v80, 0xbfb8aa3b, v64
	v_mul_f32_e32 v81, 0xbfb8aa3b, v65
	v_exp_f32_e32 v112, v112
	v_exp_f32_e32 v113, v113
	v_exp_f32_e32 v114, v114
	v_exp_f32_e32 v115, v115
	v_exp_f32_e32 v116, v116
	v_exp_f32_e32 v117, v117
	v_exp_f32_e32 v118, v118
	v_exp_f32_e32 v119, v119
	v_exp_f32_e32 v120, v120
	v_exp_f32_e32 v121, v121
	v_exp_f32_e32 v122, v122
	v_exp_f32_e32 v123, v123
	v_exp_f32_e32 v124, v124
	v_exp_f32_e32 v125, v125
	v_exp_f32_e32 v80, v80
	v_exp_f32_e32 v81, v81
	v_add_f32_e32 v112, 1.0, v112
	v_add_f32_e32 v113, 1.0, v113
	v_add_f32_e32 v114, 1.0, v114
	v_add_f32_e32 v115, 1.0, v115
	v_add_f32_e32 v116, 1.0, v116
	v_add_f32_e32 v117, 1.0, v117
	v_add_f32_e32 v118, 1.0, v118
	v_add_f32_e32 v119, 1.0, v119
	v_add_f32_e32 v120, 1.0, v120
	v_add_f32_e32 v121, 1.0, v121
	v_add_f32_e32 v122, 1.0, v122
	v_add_f32_e32 v123, 1.0, v123
	v_add_f32_e32 v124, 1.0, v124
	v_add_f32_e32 v125, 1.0, v125
	v_add_f32_e32 v80, 1.0, v80
	v_add_f32_e32 v81, 1.0, v81
	v_rcp_f32_e32 v112, v112
	v_rcp_f32_e32 v113, v113
	v_rcp_f32_e32 v114, v114
	v_rcp_f32_e32 v115, v115
	v_rcp_f32_e32 v116, v116
	v_rcp_f32_e32 v117, v117
	v_rcp_f32_e32 v118, v118
	v_rcp_f32_e32 v119, v119
	v_rcp_f32_e32 v120, v120
	v_rcp_f32_e32 v121, v121
	v_rcp_f32_e32 v122, v122
	v_rcp_f32_e32 v123, v123
	v_rcp_f32_e32 v124, v124
	v_rcp_f32_e32 v125, v125
	v_rcp_f32_e32 v80, v80
	v_rcp_f32_e32 v81, v81
	s_and_b64 vcc, exec, s[2:3]
	s_cbranch_vccz .Lact_sig_0
	v_mul_f32_e32 v112, v54, v112
	v_mul_f32_e32 v113, v55, v113
	v_mul_f32_e32 v114, v56, v114
	v_mul_f32_e32 v115, v57, v115
	v_mul_f32_e32 v116, v50, v116
	v_mul_f32_e32 v117, v51, v117
	v_mul_f32_e32 v118, v52, v118
	v_mul_f32_e32 v119, v53, v119
	v_mul_f32_e32 v120, v58, v120
	v_mul_f32_e32 v121, v59, v121
	v_mul_f32_e32 v122, v60, v122
	v_mul_f32_e32 v123, v61, v123
	v_mul_f32_e32 v124, v62, v124
	v_mul_f32_e32 v125, v63, v125
	v_mul_f32_e32 v80, v64, v80
	v_mul_f32_e32 v81, v65, v81
.Lact_sig_0:
	v_cvt_pk_bf16_f32 v214, v112, v113
	v_cvt_pk_bf16_f32 v215, v114, v115
	v_cvt_pk_bf16_f32 v216, v116, v117
	v_cvt_pk_bf16_f32 v217, v118, v119
	v_cvt_pk_bf16_f32 v222, v120, v121
	v_cvt_pk_bf16_f32 v223, v122, v123
	v_cvt_pk_bf16_f32 v224, v124, v125
	v_cvt_pk_bf16_f32 v225, v80, v81
	s_nop 1
	v_permlane16_swap_b32_e32 v214, v216
	v_permlane16_swap_b32_e32 v215, v217
	v_permlane16_swap_b32_e32 v222, v224
	v_permlane16_swap_b32_e32 v223, v225
	global_store_dwordx4 v[66:67], v[214:217], off
	global_store_dwordx4 v[66:67], v[222:225], off offset:64

; DI unsigned pk2(float a, float b) { f32x2 v = {a, b}; bfv2 r = __builtin_convertvector(v, bfv2); return __builtin_bit_cast(unsigned, r); }
; DI float sigmoidf_(float x) { return __builtin_amdgcn_rcpf(1.0f + __expf(-x)); }
; DI float siluf_(float x) { return x * __builtin_amdgcn_rcpf(1.0f + __expf(-x)); }
; DI void phase_gemm_in(const Params& p, int l, char* lds) {
;     ...
;       } else if (kind == 1 || kind == 5) {
; #pragma unroll
;         for (int ni = 0; ni < 4; ++ni) {
;           const int c = colb + ni * 16; f32x4 v = acc[mi][ni];
; #pragma unroll
;           for (int e = 0; e < 4; ++e) v[e] = (kind == 1) ? siluf_(v[e]) : sigmoidf_(v[e]);
;           u32x2 o; o[0] = pk2(v[0], v[1]); o[1] = pk2(v[2], v[3]); *(u32x2*)(zrow + c) = o;
;         }
.LBB0_118:
	s_andn2_b64 vcc, exec, s[0:1]
	s_cbranch_vccnz .LBB0_120
	v_mov_b32_e32 v0, v74
	v_lshl_add_u64 v[66:67], v[0:1], 1, v[54:55]
	v_bfe_u32 v68, v212, 4, 1
	v_mov_b32_e32 v69, 0
	v_mul_u32_u24_e32 v68, 24, v68
	v_lshl_add_u64 v[66:67], v[68:69], 0, v[66:67]
	v_mul_f32_e32 v112, 0xbfb8aa3b, v46
	v_mul_f32_e32 v113, 0xbfb8aa3b, v47
	v_mul_f32_e32 v114, 0xbfb8aa3b, v48
	v_mul_f32_e32 v115, 0xbfb8aa3b, v49
	v_mul_f32_e32 v116, 0xbfb8aa3b, v42
	v_mul_f32_e32 v117, 0xbfb8aa3b, v43
	v_mul_f32_e32 v118, 0xbfb8aa3b, v44
	v_mul_f32_e32 v119, 0xbfb8aa3b, v45
	v_mul_f32_e32 v120, 0xbfb8aa3b, v38
	v_mul_f32_e32 v121, 0xbfb8aa3b, v39
	v_mul_f32_e32 v122, 0xbfb8aa3b, v40
	v_mul_f32_e32 v123, 0xbfb8aa3b, v41
	v_mul_f32_e32 v124, 0xbfb8aa3b, v34
	v_mul_f32_e32 v125, 0xbfb8aa3b, v35
	v_mul_f32_e32 v80, 0xbfb8aa3b, v36
	v_mul_f32_e32 v81, 0xbfb8aa3b, v37
	v_exp_f32_e32 v112, v112
	v_exp_f32_e32 v113, v113
	v_exp_f32_e32 v114, v114
	v_exp_f32_e32 v115, v115
	v_exp_f32_e32 v116, v116
	v_exp_f32_e32 v117, v117
	v_exp_f32_e32 v118, v118
	v_exp_f32_e32 v119, v119
	v_exp_f32_e32 v120, v120
	v_exp_f32_e32 v121, v121
	v_exp_f32_e32 v122, v122
	v_exp_f32_e32 v123, v123
	v_exp_f32_e32 v124, v124
	v_exp_f32_e32 v125, v125
	v_exp_f32_e32 v80, v80
	v_exp_f32_e32 v81, v81
	v_add_f32_e32 v112, 1.0, v112
	v_add_f32_e32 v113, 1.0, v113
	v_add_f32_e32 v114, 1.0, v114
	v_add_f32_e32 v115, 1.0, v115
	v_add_f32_e32 v116, 1.0, v116
	v_add_f32_e32 v117, 1.0, v117
	v_add_f32_e32 v118, 1.0, v118
	v_add_f32_e32 v119, 1.0, v119
	v_add_f32_e32 v120, 1.0, v120
	v_add_f32_e32 v121, 1.0, v121
	v_add_f32_e32 v122, 1.0, v122
	v_add_f32_e32 v123, 1.0, v123
	v_add_f32_e32 v124, 1.0, v124
	v_add_f32_e32 v125, 1.0, v125
	v_add_f32_e32 v80, 1.0, v80
	v_add_f32_e32 v81, 1.0, v81
	v_rcp_f32_e32 v112, v112
	v_rcp_f32_e32 v113, v113
	v_rcp_f32_e32 v114, v114
	v_rcp_f32_e32 v115, v115
	v_rcp_f32_e32 v116, v116
	v_rcp_f32_e32 v117, v117
	v_rcp_f32_e32 v118, v118
	v_rcp_f32_e32 v119, v119
	v_rcp_f32_e32 v120, v120
	v_rcp_f32_e32 v121, v121
	v_rcp_f32_e32 v122, v122
	v_rcp_f32_e32 v123, v123
	v_rcp_f32_e32 v124, v124
	v_rcp_f32_e32 v125, v125
	v_rcp_f32_e32 v80, v80
	v_rcp_f32_e32 v81, v81
	s_and_b64 vcc, exec, s[2:3]
	s_cbranch_vccz .Lact_sig_1
	v_mul_f32_e32 v112, v46, v112
	v_mul_f32_e32 v113, v47, v113
	v_mul_f32_e32 v114, v48, v114
	v_mul_f32_e32 v115, v49, v115
	v_mul_f32_e32 v116, v42, v116
	v_mul_f32_e32 v117, v43, v117
	v_mul_f32_e32 v118, v44, v118
	v_mul_f32_e32 v119, v45, v119
	v_mul_f32_e32 v120, v38, v120
	v_mul_f32_e32 v121, v39, v121
	v_mul_f32_e32 v122, v40, v122
	v_mul_f32_e32 v123, v41, v123
	v_mul_f32_e32 v124, v34, v124
	v_mul_f32_e32 v125, v35, v125
	v_mul_f32_e32 v80, v36, v80
	v_mul_f32_e32 v81, v37, v81

; DI unsigned pk2(float a, float b) { f32x2 v = {a, b}; bfv2 r = __builtin_convertvector(v, bfv2); return __builtin_bit_cast(unsigned, r); }
; DI float sigmoidf_(float x) { return __builtin_amdgcn_rcpf(1.0f + __expf(-x)); }
; DI float siluf_(float x) { return x * __builtin_amdgcn_rcpf(1.0f + __expf(-x)); }
; DI void phase_gemm_in(const Params& p, int l, char* lds) {
;     ...
;       } else if (kind == 1 || kind == 5) {
; #pragma unroll
;         for (int ni = 0; ni < 4; ++ni) {
;           const int c = colb + ni * 16; f32x4 v = acc[mi][ni];
; #pragma unroll
;           for (int e = 0; e < 4; ++e) v[e] = (kind == 1) ? siluf_(v[e]) : sigmoidf_(v[e]);
;           u32x2 o; o[0] = pk2(v[0], v[1]); o[1] = pk2(v[2], v[3]); *(u32x2*)(zrow + c) = o;
;         }
.LBB0_141:
	s_andn2_b64 vcc, exec, s[0:1]
	s_cbranch_vccnz .LBB0_143
	v_mov_b32_e32 v0, v74
	v_lshl_add_u64 v[66:67], v[0:1], 1, v[38:39]
	v_bfe_u32 v68, v212, 4, 1
	v_mov_b32_e32 v69, 0
	v_mul_u32_u24_e32 v68, 24, v68
	v_lshl_add_u64 v[66:67], v[68:69], 0, v[66:67]
	v_mul_f32_e32 v112, 0xbfb8aa3b, v30
	v_mul_f32_e32 v113, 0xbfb8aa3b, v31
	v_mul_f32_e32 v114, 0xbfb8aa3b, v32
	v_mul_f32_e32 v115, 0xbfb8aa3b, v33
	v_mul_f32_e32 v116, 0xbfb8aa3b, v22
	v_mul_f32_e32 v117, 0xbfb8aa3b, v23
	v_mul_f32_e32 v118, 0xbfb8aa3b, v24
	v_mul_f32_e32 v119, 0xbfb8aa3b, v25
	v_mul_f32_e32 v120, 0xbfb8aa3b, v26
	v_mul_f32_e32 v121, 0xbfb8aa3b, v27
	v_mul_f32_e32 v122, 0xbfb8aa3b, v28
	v_mul_f32_e32 v123, 0xbfb8aa3b, v29
	v_mul_f32_e32 v124, 0xbfb8aa3b, v18
	v_mul_f32_e32 v125, 0xbfb8aa3b, v19
	v_mul_f32_e32 v80, 0xbfb8aa3b, v20
	v_mul_f32_e32 v81, 0xbfb8aa3b, v21
	v_exp_f32_e32 v112, v112
	v_exp_f32_e32 v113, v113
	v_exp_f32_e32 v114, v114
	v_exp_f32_e32 v115, v115
	v_exp_f32_e32 v116, v116
	v_exp_f32_e32 v117, v117
	v_exp_f32_e32 v118, v118
	v_exp_f32_e32 v119, v119
	v_exp_f32_e32 v120, v120
	v_exp_f32_e32 v121, v121
	v_exp_f32_e32 v122, v122
	v_exp_f32_e32 v123, v123
	v_exp_f32_e32 v124, v124
	v_exp_f32_e32 v125, v125
	v_exp_f32_e32 v80, v80
	v_exp_f32_e32 v81, v81
	v_add_f32_e32 v112, 1.0, v112
	v_add_f32_e32 v113, 1.0, v113
	v_add_f32_e32 v114, 1.0, v114
	v_add_f32_e32 v115, 1.0, v115
	v_add_f32_e32 v116, 1.0, v116
	v_add_f32_e32 v117, 1.0, v117
	v_add_f32_e32 v118, 1.0, v118
	v_add_f32_e32 v119, 1.0, v119
	v_add_f32_e32 v120, 1.0, v120
	v_add_f32_e32 v121, 1.0, v121
	v_add_f32_e32 v122, 1.0, v122
	v_add_f32_e32 v123, 1.0, v123
	v_add_f32_e32 v124, 1.0, v124
	v_add_f32_e32 v125, 1.0, v125
	v_add_f32_e32 v80, 1.0, v80
	v_add_f32_e32 v81, 1.0, v81
	v_rcp_f32_e32 v112, v112
	v_rcp_f32_e32 v113, v113
	v_rcp_f32_e32 v114, v114
	v_rcp_f32_e32 v115, v115
	v_rcp_f32_e32 v116, v116
	v_rcp_f32_e32 v117, v117
	v_rcp_f32_e32 v118, v118
	v_rcp_f32_e32 v119, v119
	v_rcp_f32_e32 v120, v120
	v_rcp_f32_e32 v121, v121
	v_rcp_f32_e32 v122, v122
	v_rcp_f32_e32 v123, v123
	v_rcp_f32_e32 v124, v124
	v_rcp_f32_e32 v125, v125
	v_rcp_f32_e32 v80, v80
	v_rcp_f32_e32 v81, v81
	s_and_b64 vcc, exec, s[2:3]
	s_cbranch_vccz .Lact_sig_2
	v_mul_f32_e32 v112, v30, v112
	v_mul_f32_e32 v113, v31, v113
	v_mul_f32_e32 v114, v32, v114
	v_mul_f32_e32 v115, v33, v115
	v_mul_f32_e32 v116, v22, v116
	v_mul_f32_e32 v117, v23, v117
	v_mul_f32_e32 v118, v24, v118
	v_mul_f32_e32 v119, v25, v119
	v_mul_f32_e32 v120, v26, v120
	v_mul_f32_e32 v121, v27, v121
	v_mul_f32_e32 v122, v28, v122
	v_mul_f32_e32 v123, v29, v123
	v_mul_f32_e32 v124, v18, v124
	v_mul_f32_e32 v125, v19, v125
	v_mul_f32_e32 v80, v20, v80
	v_mul_f32_e32 v81, v21, v81

; DI unsigned pk2(float a, float b) { f32x2 v = {a, b}; bfv2 r = __builtin_convertvector(v, bfv2); return __builtin_bit_cast(unsigned, r); }
; DI float sigmoidf_(float x) { return __builtin_amdgcn_rcpf(1.0f + __expf(-x)); }
; DI float siluf_(float x) { return x * __builtin_amdgcn_rcpf(1.0f + __expf(-x)); }
; DI void phase_gemm_in(const Params& p, int l, char* lds) {
;     ...
;       } else if (kind == 1 || kind == 5) {
; #pragma unroll
;         for (int ni = 0; ni < 4; ++ni) {
;           const int c = colb + ni * 16; f32x4 v = acc[mi][ni];
; #pragma unroll
;           for (int e = 0; e < 4; ++e) v[e] = (kind == 1) ? siluf_(v[e]) : sigmoidf_(v[e]);
;           u32x2 o; o[0] = pk2(v[0], v[1]); o[1] = pk2(v[2], v[3]); *(u32x2*)(zrow + c) = o;
;         }
.LBB0_164:
	s_andn2_b64 vcc, exec, s[30:31]
	s_cbranch_vccnz .LBB0_166
	v_mov_b32_e32 v0, v74
	v_lshl_add_u64 v[66:67], v[0:1], 1, v[22:23]
	v_bfe_u32 v68, v212, 4, 1
	v_mov_b32_e32 v69, 0
	v_mul_u32_u24_e32 v68, 24, v68
	v_lshl_add_u64 v[66:67], v[68:69], 0, v[66:67]
	v_mul_f32_e32 v112, 0xbfb8aa3b, v14
	v_mul_f32_e32 v113, 0xbfb8aa3b, v15
	v_mul_f32_e32 v114, 0xbfb8aa3b, v16
	v_mul_f32_e32 v115, 0xbfb8aa3b, v17
	v_mul_f32_e32 v116, 0xbfb8aa3b, v10
	v_mul_f32_e32 v117, 0xbfb8aa3b, v11
	v_mul_f32_e32 v118, 0xbfb8aa3b, v12
	v_mul_f32_e32 v119, 0xbfb8aa3b, v13
	v_mul_f32_e32 v120, 0xbfb8aa3b, v6
	v_mul_f32_e32 v121, 0xbfb8aa3b, v7
	v_mul_f32_e32 v122, 0xbfb8aa3b, v8
	v_mul_f32_e32 v123, 0xbfb8aa3b, v9
	v_mul_f32_e32 v124, 0xbfb8aa3b, v2
	v_mul_f32_e32 v125, 0xbfb8aa3b, v3
	v_mul_f32_e32 v80, 0xbfb8aa3b, v4
	v_mul_f32_e32 v81, 0xbfb8aa3b, v5
	v_exp_f32_e32 v112, v112
	v_exp_f32_e32 v113, v113
	v_exp_f32_e32 v114, v114
	v_exp_f32_e32 v115, v115
	v_exp_f32_e32 v116, v116
	v_exp_f32_e32 v117, v117
	v_exp_f32_e32 v118, v118
	v_exp_f32_e32 v119, v119
	v_exp_f32_e32 v120, v120
	v_exp_f32_e32 v121, v121
	v_exp_f32_e32 v122, v122
	v_exp_f32_e32 v123, v123
	v_exp_f32_e32 v124, v124
	v_exp_f32_e32 v125, v125
	v_exp_f32_e32 v80, v80
	v_exp_f32_e32 v81, v81
	v_add_f32_e32 v112, 1.0, v112
	v_add_f32_e32 v113, 1.0, v113
	v_add_f32_e32 v114, 1.0, v114
	v_add_f32_e32 v115, 1.0, v115
	v_add_f32_e32 v116, 1.0, v116
	v_add_f32_e32 v117, 1.0, v117
	v_add_f32_e32 v118, 1.0, v118
	v_add_f32_e32 v119, 1.0, v119
	v_add_f32_e32 v120, 1.0, v120
	v_add_f32_e32 v121, 1.0, v121
	v_add_f32_e32 v122, 1.0, v122
	v_add_f32_e32 v123, 1.0, v123
	v_add_f32_e32 v124, 1.0, v124
	v_add_f32_e32 v125, 1.0, v125
	v_add_f32_e32 v80, 1.0, v80
	v_add_f32_e32 v81, 1.0, v81
	v_rcp_f32_e32 v112, v112
	v_rcp_f32_e32 v113, v113
	v_rcp_f32_e32 v114, v114
	v_rcp_f32_e32 v115, v115
	v_rcp_f32_e32 v116, v116
	v_rcp_f32_e32 v117, v117
	v_rcp_f32_e32 v118, v118
	v_rcp_f32_e32 v119, v119
	v_rcp_f32_e32 v120, v120
	v_rcp_f32_e32 v121, v121
	v_rcp_f32_e32 v122, v122
	v_rcp_f32_e32 v123, v123
	v_rcp_f32_e32 v124, v124
	v_rcp_f32_e32 v125, v125
	v_rcp_f32_e32 v80, v80
	v_rcp_f32_e32 v81, v81
	s_and_b64 vcc, exec, s[2:3]
	s_cbranch_vccz .Lact_sig_3
	v_mul_f32_e32 v112, v14, v112
	v_mul_f32_e32 v113, v15, v113
	v_mul_f32_e32 v114, v16, v114
	v_mul_f32_e32 v115, v17, v115
	v_mul_f32_e32 v116, v10, v116
	v_mul_f32_e32 v117, v11, v117
	v_mul_f32_e32 v118, v12, v118
	v_mul_f32_e32 v119, v13, v119
	v_mul_f32_e32 v120, v6, v120
	v_mul_f32_e32 v121, v7, v121
	v_mul_f32_e32 v122, v8, v122
	v_mul_f32_e32 v123, v9, v123
	v_mul_f32_e32 v124, v2, v124
	v_mul_f32_e32 v125, v3, v125
	v_mul_f32_e32 v80, v4, v80
	v_mul_f32_e32 v81, v5, v81
